# side-job v_max3 consume moved from MFMA segment head into the MFMA stream (3 K-loops); accumulator zeroing with v_mov_b64
# speedup vs baseline: 1.0077x; 1.0077x over previous
.LBB0_236:
	s_add_i32 s12, s75, 2
	s_add_u32 s30, s28, 0xfff00080
	s_addc_u32 s31, s29, -1
	s_cmp_eq_u32 s72, s75
	s_cselect_b32 s35, s68, s31
	s_cselect_b32 s34, s69, s30
	s_cselect_b32 s31, s70, s74
	s_cselect_b32 s30, s71, s73
	s_cmpk_lt_i32 s3, 0x56
	s_cselect_b32 s36, s58, 0x2b00
	s_mov_b32 s37, 0xac00
	s_cselect_b32 s75, s37, 0x4000
	s_sub_i32 s36, s36, s33
	v_min3_i32 v5, s36, v174, 2
	v_sub_u32_e32 v174, v174, v5
	v_readfirstlane_b32 s78, v5
	s_max_i32 s36, s78, 0
	s_add_i32 s36, s33, s36
	s_add_i32 s76, s36, -1
	s_min_i32 s36, s33, s76
	s_mul_hi_i32 s37, s75, s36
	s_mul_i32 s36, s75, s36
	s_add_u32 s36, s38, s36
	s_addc_u32 s37, s39, s37
	s_mul_hi_i32 s77, s75, s76
	s_mul_i32 s75, s75, s76
	s_add_u32 s76, s38, s75
	global_load_dwordx4 v[152:155], v173, s[36:37] nt
	s_addc_u32 s77, s39, s77
	global_load_dwordx4 v[164:167], v173, s[76:77] nt
	s_add_i32 s33, s78, s33
	v_add_u32_e32 v5, s59, v160
	ds_read_b128 v[168:171], v5
	ds_read_b128 v[176:179], v5 offset:1024
	ds_read_b128 v[180:183], v5 offset:2048
	ds_read_b128 v[184:187], v5 offset:3072
	v_add_u32_e32 v5, s60, v160
	ds_read_b128 v[188:191], v5
	ds_read_b128 v[192:195], v5 offset:1024
	ds_read_b128 v[196:199], v5 offset:2048
	ds_read_b128 v[200:203], v5 offset:3072
	v_lshl_add_u64 v[6:7], s[28:29], 0, v[146:147]
	s_add_i32 m0, s49, 0xc000
	ds_read_b128 v[204:207], v163
	ds_read_b128 v[208:211], v163 offset:1024
	ds_read_b128 v[212:215], v163 offset:2048
	ds_read_b128 v[216:219], v163 offset:3072
	ds_read_b128 v[220:223], v163 offset:4096
	ds_read_b128 v[224:227], v163 offset:5120
	ds_read_b128 v[228:231], v163 offset:6144
	ds_read_b128 v[236:239], v163 offset:7168
	global_load_lds_dwordx4 v[6:7], off
	v_lshl_add_u64 v[6:7], s[28:29], 0, v[148:149]
	s_add_i32 m0, s49, 0xe000
	s_nop 0
	global_load_lds_dwordx4 v[6:7], off
	s_waitcnt vmcnt(10)
	s_waitcnt lgkmcnt(0)
	s_barrier
	s_setprio 1
	s_waitcnt lgkmcnt(0)
	v_mfma_f32_16x16x32_bf16 v[132:135], v[168:171], v[204:207], v[132:135]
	v_mfma_f32_16x16x32_bf16 v[128:131], v[180:183], v[204:207], v[128:131]
	v_mfma_f32_16x16x32_bf16 v[116:119], v[168:171], v[212:215], v[116:119]
	v_mfma_f32_16x16x32_bf16 v[112:115], v[180:183], v[212:215], v[112:115]
	v_mfma_f32_16x16x32_bf16 v[100:103], v[168:171], v[220:223], v[100:103]
	v_mfma_f32_16x16x32_bf16 v[96:99], v[180:183], v[220:223], v[96:99]
	v_mfma_f32_16x16x32_bf16 v[84:87], v[168:171], v[228:231], v[84:87]
	v_mfma_f32_16x16x32_bf16 v[80:83], v[180:183], v[228:231], v[80:83]
	v_mfma_f32_16x16x32_bf16 v[132:135], v[176:179], v[208:211], v[132:135]
	v_mfma_f32_16x16x32_bf16 v[128:131], v[184:187], v[208:211], v[128:131]
	v_mfma_f32_16x16x32_bf16 v[116:119], v[176:179], v[216:219], v[116:119]
	v_mfma_f32_16x16x32_bf16 v[112:115], v[184:187], v[216:219], v[112:115]
	v_mfma_f32_16x16x32_bf16 v[100:103], v[176:179], v[224:227], v[100:103]
	v_mfma_f32_16x16x32_bf16 v[96:99], v[184:187], v[224:227], v[96:99]
	v_mfma_f32_16x16x32_bf16 v[84:87], v[176:179], v[236:239], v[84:87]
	v_mfma_f32_16x16x32_bf16 v[80:83], v[184:187], v[236:239], v[80:83]
	s_setprio 0
	s_setprio 1
	v_mfma_f32_16x16x32_bf16 v[124:127], v[188:191], v[204:207], v[124:127]
	v_mfma_f32_16x16x32_bf16 v[120:123], v[196:199], v[204:207], v[120:123]
	v_mfma_f32_16x16x32_bf16 v[108:111], v[188:191], v[212:215], v[108:111]
	v_mfma_f32_16x16x32_bf16 v[104:107], v[196:199], v[212:215], v[104:107]
	v_mfma_f32_16x16x32_bf16 v[92:95], v[188:191], v[220:223], v[92:95]
	v_mfma_f32_16x16x32_bf16 v[88:91], v[196:199], v[220:223], v[88:91]
	v_mfma_f32_16x16x32_bf16 v[76:79], v[188:191], v[228:231], v[76:79]
	v_mfma_f32_16x16x32_bf16 v[72:75], v[196:199], v[228:231], v[72:75]
	v_mfma_f32_16x16x32_bf16 v[124:127], v[192:195], v[208:211], v[124:127]
	v_mfma_f32_16x16x32_bf16 v[120:123], v[200:203], v[208:211], v[120:123]
	v_mfma_f32_16x16x32_bf16 v[108:111], v[192:195], v[216:219], v[108:111]
	v_mfma_f32_16x16x32_bf16 v[104:107], v[200:203], v[216:219], v[104:107]
	v_mfma_f32_16x16x32_bf16 v[92:95], v[192:195], v[224:227], v[92:95]
	v_mfma_f32_16x16x32_bf16 v[88:91], v[200:203], v[224:227], v[88:91]
	v_mfma_f32_16x16x32_bf16 v[76:79], v[192:195], v[236:239], v[76:79]
	v_mfma_f32_16x16x32_bf16 v[72:75], v[200:203], v[236:239], v[72:75]
	s_setprio 0
	s_barrier
	s_add_i32 s36, s59, s48
	v_lshl_add_u64 v[156:157], s[30:31], 0, v[138:139]
	s_mov_b32 m0, s36
	ds_read_b128 v[204:207], v163 offset:16384
	ds_read_b128 v[208:211], v163 offset:17408
	ds_read_b128 v[212:215], v163 offset:18432
	ds_read_b128 v[216:219], v163 offset:19456
	ds_read_b128 v[220:223], v163 offset:20480
	ds_read_b128 v[224:227], v163 offset:21504
	ds_read_b128 v[228:231], v163 offset:22528
	ds_read_b128 v[236:239], v163 offset:23552
	global_load_lds_dwordx4 v[156:157], off
	s_add_i32 m0, s36, 0x2000
	s_add_u32 s36, s30, 0x100000
	v_lshl_add_u64 v[232:233], s[30:31], 0, v[142:143]
	s_addc_u32 s37, s31, 0
	s_add_i32 s75, s60, s48
	global_load_lds_dwordx4 v[232:233], off
	v_lshl_add_u64 v[6:7], s[36:37], 0, v[138:139]
	s_mov_b32 m0, s75
	v_lshl_add_u64 v[240:241], s[34:35], 0, v[136:137]
	global_load_lds_dwordx4 v[6:7], off
	v_lshl_add_u64 v[6:7], s[36:37], 0, v[142:143]
	s_add_i32 m0, s75, 0x2000
	v_lshl_add_u64 v[242:243], s[34:35], 0, v[140:141]
	global_load_lds_dwordx4 v[6:7], off
	s_mov_b32 m0, s49
	s_nop 0
	global_load_lds_dwordx4 v[240:241], off
	s_mov_b32 m0, s50
	s_nop 0
	global_load_lds_dwordx4 v[242:243], off
	s_waitcnt vmcnt(10)
	s_waitcnt lgkmcnt(0)
	s_barrier
	s_setprio 1
	s_waitcnt lgkmcnt(0)
	v_mfma_f32_16x16x32_bf16 v[68:71], v[168:171], v[204:207], v[68:71]
	v_mfma_f32_16x16x32_bf16 v[64:67], v[180:183], v[204:207], v[64:67]
	v_mfma_f32_16x16x32_bf16 v[52:55], v[168:171], v[212:215], v[52:55]
	v_mfma_f32_16x16x32_bf16 v[48:51], v[180:183], v[212:215], v[48:51]
	v_mfma_f32_16x16x32_bf16 v[36:39], v[168:171], v[220:223], v[36:39]
	v_mfma_f32_16x16x32_bf16 v[32:35], v[180:183], v[220:223], v[32:35]
	v_mfma_f32_16x16x32_bf16 v[20:23], v[168:171], v[228:231], v[20:23]
	v_mfma_f32_16x16x32_bf16 v[16:19], v[180:183], v[228:231], v[16:19]
	v_mfma_f32_16x16x32_bf16 v[68:71], v[176:179], v[208:211], v[68:71]
	v_mfma_f32_16x16x32_bf16 v[64:67], v[184:187], v[208:211], v[64:67]
	v_mfma_f32_16x16x32_bf16 v[52:55], v[176:179], v[216:219], v[52:55]
	v_mfma_f32_16x16x32_bf16 v[48:51], v[184:187], v[216:219], v[48:51]
	v_mfma_f32_16x16x32_bf16 v[36:39], v[176:179], v[224:227], v[36:39]
	v_mfma_f32_16x16x32_bf16 v[32:35], v[184:187], v[224:227], v[32:35]
	v_mfma_f32_16x16x32_bf16 v[20:23], v[176:179], v[236:239], v[20:23]
	v_mfma_f32_16x16x32_bf16 v[16:19], v[184:187], v[236:239], v[16:19]
	s_setprio 0
	s_setprio 1
	v_mfma_f32_16x16x32_bf16 v[60:63], v[188:191], v[204:207], v[60:63]
	v_mfma_f32_16x16x32_bf16 v[56:59], v[196:199], v[204:207], v[56:59]
	v_mfma_f32_16x16x32_bf16 v[44:47], v[188:191], v[212:215], v[44:47]
	v_mfma_f32_16x16x32_bf16 v[40:43], v[196:199], v[212:215], v[40:43]
	v_mfma_f32_16x16x32_bf16 v[28:31], v[188:191], v[220:223], v[28:31]
	v_mfma_f32_16x16x32_bf16 v[24:27], v[196:199], v[220:223], v[24:27]
	v_mfma_f32_16x16x32_bf16 v[12:15], v[188:191], v[228:231], v[12:15]
	v_mfma_f32_16x16x32_bf16 v[6:9], v[196:199], v[228:231], v[8:11]
	v_mfma_f32_16x16x32_bf16 v[60:63], v[192:195], v[208:211], v[60:63]
	v_mfma_f32_16x16x32_bf16 v[56:59], v[200:203], v[208:211], v[56:59]
	v_mfma_f32_16x16x32_bf16 v[44:47], v[192:195], v[216:219], v[44:47]
	v_mfma_f32_16x16x32_bf16 v[40:43], v[200:203], v[216:219], v[40:43]
	v_mfma_f32_16x16x32_bf16 v[28:31], v[192:195], v[224:227], v[28:31]
	v_mfma_f32_16x16x32_bf16 v[24:27], v[200:203], v[224:227], v[24:27]
	v_mfma_f32_16x16x32_bf16 v[12:15], v[192:195], v[236:239], v[12:15]
	v_mfma_f32_16x16x32_bf16 v[6:9], v[200:203], v[236:239], v[6:9]
	s_setprio 0
	s_barrier
	s_add_i32 s36, 0, 0x18000
	v_add_u32_e32 v5, s36, v160
	s_add_i32 s37, 0, 0x1c000
	ds_read_b128 v[168:171], v5
	ds_read_b128 v[176:179], v5 offset:1024
	ds_read_b128 v[180:183], v5 offset:2048
	ds_read_b128 v[184:187], v5 offset:3072
	v_add_u32_e32 v5, s37, v160
	ds_read_b128 v[188:191], v5
	ds_read_b128 v[192:195], v5 offset:1024
	ds_read_b128 v[196:199], v5 offset:2048
	ds_read_b128 v[200:203], v5 offset:3072
	s_add_u32 s34, s34, 0x100000
	s_addc_u32 s35, s35, 0
	s_mov_b32 m0, s51
	v_lshl_add_u64 v[10:11], s[34:35], 0, v[136:137]
	ds_read_b128 v[204:207], v163 offset:32768
	ds_read_b128 v[208:211], v163 offset:33792
	ds_read_b128 v[212:215], v163 offset:34816
	ds_read_b128 v[216:219], v163 offset:35840
	ds_read_b128 v[220:223], v163 offset:36864
	ds_read_b128 v[224:227], v163 offset:37888
	ds_read_b128 v[228:231], v163 offset:38912
	ds_read_b128 v[236:239], v163 offset:39936
	global_load_lds_dwordx4 v[10:11], off
	v_lshl_add_u64 v[10:11], s[34:35], 0, v[140:141]
	s_mov_b32 m0, s52
	s_nop 0
	global_load_lds_dwordx4 v[10:11], off
	s_waitcnt vmcnt(8)
	s_waitcnt lgkmcnt(0)
	s_barrier
	s_setprio 1
	s_waitcnt lgkmcnt(0)
	v_mfma_f32_16x16x32_bf16 v[132:135], v[168:171], v[204:207], v[132:135]
	v_mfma_f32_16x16x32_bf16 v[128:131], v[180:183], v[204:207], v[128:131]
	v_mfma_f32_16x16x32_bf16 v[116:119], v[168:171], v[212:215], v[116:119]
	v_mfma_f32_16x16x32_bf16 v[112:115], v[180:183], v[212:215], v[112:115]
	v_mfma_f32_16x16x32_bf16 v[100:103], v[168:171], v[220:223], v[100:103]
	v_max3_f32 v0, v0, |v152|, |v164|
	v_mfma_f32_16x16x32_bf16 v[96:99], v[180:183], v[220:223], v[96:99]
	v_max3_f32 v1, v1, |v153|, |v165|
	v_mfma_f32_16x16x32_bf16 v[84:87], v[168:171], v[228:231], v[84:87]
	v_max3_f32 v2, v2, |v154|, |v166|
	v_mfma_f32_16x16x32_bf16 v[80:83], v[180:183], v[228:231], v[80:83]
	v_max3_f32 v3, v3, |v155|, |v167|
	v_mfma_f32_16x16x32_bf16 v[132:135], v[176:179], v[208:211], v[132:135]
	v_mfma_f32_16x16x32_bf16 v[128:131], v[184:187], v[208:211], v[128:131]
	v_mfma_f32_16x16x32_bf16 v[116:119], v[176:179], v[216:219], v[116:119]
	v_mfma_f32_16x16x32_bf16 v[112:115], v[184:187], v[216:219], v[112:115]
	v_mfma_f32_16x16x32_bf16 v[100:103], v[176:179], v[224:227], v[100:103]
	v_mfma_f32_16x16x32_bf16 v[96:99], v[184:187], v[224:227], v[96:99]
	v_mfma_f32_16x16x32_bf16 v[84:87], v[176:179], v[236:239], v[84:87]
	v_mfma_f32_16x16x32_bf16 v[80:83], v[184:187], v[236:239], v[80:83]
	s_setprio 0
	s_setprio 1
	v_mfma_f32_16x16x32_bf16 v[124:127], v[188:191], v[204:207], v[124:127]
	v_mfma_f32_16x16x32_bf16 v[120:123], v[196:199], v[204:207], v[120:123]
	v_mfma_f32_16x16x32_bf16 v[108:111], v[188:191], v[212:215], v[108:111]
	v_mfma_f32_16x16x32_bf16 v[104:107], v[196:199], v[212:215], v[104:107]
	v_mfma_f32_16x16x32_bf16 v[92:95], v[188:191], v[220:223], v[92:95]
	v_mfma_f32_16x16x32_bf16 v[88:91], v[196:199], v[220:223], v[88:91]
	v_mfma_f32_16x16x32_bf16 v[76:79], v[188:191], v[228:231], v[76:79]
	v_mfma_f32_16x16x32_bf16 v[72:75], v[196:199], v[228:231], v[72:75]
	v_mfma_f32_16x16x32_bf16 v[124:127], v[192:195], v[208:211], v[124:127]
	v_mfma_f32_16x16x32_bf16 v[120:123], v[200:203], v[208:211], v[120:123]
	v_mfma_f32_16x16x32_bf16 v[108:111], v[192:195], v[216:219], v[108:111]
	v_mfma_f32_16x16x32_bf16 v[104:107], v[200:203], v[216:219], v[104:107]
	v_mfma_f32_16x16x32_bf16 v[92:95], v[192:195], v[224:227], v[92:95]
	v_mfma_f32_16x16x32_bf16 v[88:91], v[200:203], v[224:227], v[88:91]
	v_mfma_f32_16x16x32_bf16 v[76:79], v[192:195], v[236:239], v[76:79]
	v_mfma_f32_16x16x32_bf16 v[72:75], v[200:203], v[236:239], v[72:75]
	s_setprio 0
	s_barrier
	s_add_i32 s34, s36, s48
	v_lshl_add_u64 v[10:11], v[156:157], 0, s[10:11]
	s_mov_b32 m0, s34
	ds_read_b128 v[152:155], v163 offset:49152
	ds_read_b128 v[164:167], v163 offset:50176
	ds_read_b128 v[204:207], v163 offset:51200
	ds_read_b128 v[208:211], v163 offset:52224
	ds_read_b128 v[212:215], v163 offset:53248
	ds_read_b128 v[216:219], v163 offset:54272
	ds_read_b128 v[220:223], v163 offset:55296
	ds_read_b128 v[224:227], v163 offset:56320
	global_load_lds_dwordx4 v[10:11], off
	s_add_i32 m0, s34, 0x2000
	s_add_u32 s30, s30, 0x100080
	v_lshl_add_u64 v[10:11], v[232:233], 0, s[10:11]
	s_addc_u32 s31, s31, 0
	s_add_i32 s34, s37, s48
	global_load_lds_dwordx4 v[10:11], off
	v_lshl_add_u64 v[10:11], s[30:31], 0, v[138:139]
	s_mov_b32 m0, s34
	s_nop 0
	global_load_lds_dwordx4 v[10:11], off
	v_lshl_add_u64 v[10:11], s[30:31], 0, v[142:143]
	s_add_i32 m0, s34, 0x2000
	s_nop 0
	global_load_lds_dwordx4 v[10:11], off
	v_lshl_add_u64 v[10:11], v[240:241], 0, s[10:11]
	s_mov_b32 m0, s56
	s_nop 0
	global_load_lds_dwordx4 v[10:11], off
	v_lshl_add_u64 v[10:11], v[242:243], 0, s[10:11]
	s_mov_b32 m0, s57
	s_nop 0
	global_load_lds_dwordx4 v[10:11], off
	s_waitcnt vmcnt(8)
	s_waitcnt lgkmcnt(0)
	s_barrier
	s_setprio 1
	s_waitcnt lgkmcnt(0)
	v_mfma_f32_16x16x32_bf16 v[68:71], v[168:171], v[152:155], v[68:71]
	v_mfma_f32_16x16x32_bf16 v[64:67], v[180:183], v[152:155], v[64:67]
	v_mfma_f32_16x16x32_bf16 v[52:55], v[168:171], v[204:207], v[52:55]
	v_mfma_f32_16x16x32_bf16 v[48:51], v[180:183], v[204:207], v[48:51]
	v_mfma_f32_16x16x32_bf16 v[36:39], v[168:171], v[212:215], v[36:39]
	v_mfma_f32_16x16x32_bf16 v[32:35], v[180:183], v[212:215], v[32:35]
	v_mfma_f32_16x16x32_bf16 v[20:23], v[168:171], v[220:223], v[20:23]
	v_mfma_f32_16x16x32_bf16 v[16:19], v[180:183], v[220:223], v[16:19]
	v_mfma_f32_16x16x32_bf16 v[68:71], v[176:179], v[164:167], v[68:71]
	v_mfma_f32_16x16x32_bf16 v[64:67], v[184:187], v[164:167], v[64:67]
	v_mfma_f32_16x16x32_bf16 v[52:55], v[176:179], v[208:211], v[52:55]
	v_mfma_f32_16x16x32_bf16 v[48:51], v[184:187], v[208:211], v[48:51]
	v_mfma_f32_16x16x32_bf16 v[36:39], v[176:179], v[216:219], v[36:39]
	v_mfma_f32_16x16x32_bf16 v[32:35], v[184:187], v[216:219], v[32:35]
	v_mfma_f32_16x16x32_bf16 v[20:23], v[176:179], v[224:227], v[20:23]
	v_mfma_f32_16x16x32_bf16 v[16:19], v[184:187], v[224:227], v[16:19]
	s_setprio 0
	s_setprio 1
	v_mfma_f32_16x16x32_bf16 v[60:63], v[188:191], v[152:155], v[60:63]
	v_mfma_f32_16x16x32_bf16 v[56:59], v[196:199], v[152:155], v[56:59]
	v_mfma_f32_16x16x32_bf16 v[44:47], v[188:191], v[204:207], v[44:47]
	v_mfma_f32_16x16x32_bf16 v[40:43], v[196:199], v[204:207], v[40:43]
	v_mfma_f32_16x16x32_bf16 v[28:31], v[188:191], v[212:215], v[28:31]
	v_mfma_f32_16x16x32_bf16 v[24:27], v[196:199], v[212:215], v[24:27]
	v_mfma_f32_16x16x32_bf16 v[10:13], v[188:191], v[220:223], v[12:15]
	v_mfma_f32_16x16x32_bf16 v[6:9], v[196:199], v[220:223], v[6:9]
	v_mfma_f32_16x16x32_bf16 v[60:63], v[192:195], v[164:167], v[60:63]
	v_mfma_f32_16x16x32_bf16 v[56:59], v[200:203], v[164:167], v[56:59]
	v_mfma_f32_16x16x32_bf16 v[44:47], v[192:195], v[208:211], v[44:47]
	v_mfma_f32_16x16x32_bf16 v[40:43], v[200:203], v[208:211], v[40:43]
	v_mfma_f32_16x16x32_bf16 v[28:31], v[192:195], v[216:219], v[28:31]
	v_mfma_f32_16x16x32_bf16 v[24:27], v[200:203], v[216:219], v[24:27]
	v_mfma_f32_16x16x32_bf16 v[12:15], v[192:195], v[224:227], v[10:13]
	v_mfma_f32_16x16x32_bf16 v[8:11], v[200:203], v[224:227], v[6:9]
	s_setprio 0
	s_barrier
	s_add_u32 s28, s28, 0x100
	s_addc_u32 s29, s29, 0
	s_add_u32 s73, s73, 0x100
	s_addc_u32 s74, s74, 0
	s_cmp_ge_i32 s12, s67
	s_cbranch_scc0 .LBB0_221
	s_and_b64 vcc, exec, s[14:15]
	s_cbranch_vccz .LBB0_239

.LBB0_310:
	s_lshl_b32 s8, s63, 20
	s_and_b32 s8, s8, 0xff00000
	v_readlane_b32 s24, v254, 26
	v_readlane_b32 s25, v254, 27
	s_add_u32 s8, s24, s8
	s_addc_u32 s25, s25, 0
	s_lshl_b32 s24, s64, 7
	s_and_b32 s26, s24, 0x7fff80
	s_add_u32 s24, s8, s26
	s_addc_u32 s25, s25, 0
	s_lshl_b32 s8, s63, 12
	s_and_b32 s8, s8, 0xff00000
	v_readlane_b32 s66, v254, 4
	v_readlane_b32 s67, v254, 5
	s_add_u32 s8, s66, s8
	s_addc_u32 s27, s67, 0
	s_add_u32 s26, s8, s26
	s_addc_u32 s27, s27, 0
	s_ashr_i32 s66, s36, 16
	s_cmp_lt_i32 s66, 1
	s_cbranch_scc1 .LBB0_355
	s_and_b64 s[36:37], s[28:29], exec
	s_cselect_b32 s67, s25, s31
	s_cselect_b32 s68, s24, s30
	s_cselect_b32 s69, s27, s35
	s_cselect_b32 s70, s26, s34
	s_add_i32 s71, s66, -2
	s_add_u32 s30, s30, 0x80080
	s_addc_u32 s31, s31, 0
	s_add_u32 s72, s34, 0x100
	s_addc_u32 s73, s35, 0
	s_mov_b32 s74, 0
	v_mov_b64_e32 v[8:9], 0
	v_mov_b64_e32 v[10:11], 0
	v_mov_b64_e32 v[12:13], 0
	v_mov_b64_e32 v[14:15], 0
	v_mov_b64_e32 v[16:17], 0
	v_mov_b64_e32 v[18:19], 0
	v_mov_b64_e32 v[20:21], 0
	v_mov_b64_e32 v[22:23], 0
	v_mov_b64_e32 v[28:29], 0
	v_mov_b64_e32 v[30:31], 0
	v_mov_b64_e32 v[36:37], 0
	v_mov_b64_e32 v[38:39], 0
	v_mov_b64_e32 v[44:45], 0
	v_mov_b64_e32 v[46:47], 0
	v_mov_b64_e32 v[52:53], 0
	v_mov_b64_e32 v[54:55], 0
	v_mov_b64_e32 v[24:25], 0
	v_mov_b64_e32 v[26:27], 0
	v_mov_b64_e32 v[32:33], 0
	v_mov_b64_e32 v[34:35], 0
	v_mov_b64_e32 v[40:41], 0
	v_mov_b64_e32 v[42:43], 0
	v_mov_b64_e32 v[48:49], 0
	v_mov_b64_e32 v[50:51], 0
	v_mov_b64_e32 v[56:57], 0
	v_mov_b64_e32 v[58:59], 0
	v_mov_b64_e32 v[60:61], 0
	v_mov_b64_e32 v[62:63], 0
	v_mov_b64_e32 v[64:65], 0
	v_mov_b64_e32 v[66:67], 0
	v_mov_b64_e32 v[68:69], 0
	v_mov_b64_e32 v[70:71], 0
	v_mov_b64_e32 v[72:73], 0
	v_mov_b64_e32 v[74:75], 0
	v_mov_b64_e32 v[76:77], 0
	v_mov_b64_e32 v[78:79], 0
	v_mov_b64_e32 v[80:81], 0
	v_mov_b64_e32 v[82:83], 0
	v_mov_b64_e32 v[84:85], 0
	v_mov_b64_e32 v[86:87], 0
	v_mov_b64_e32 v[92:93], 0
	v_mov_b64_e32 v[94:95], 0
	v_mov_b64_e32 v[100:101], 0
	v_mov_b64_e32 v[102:103], 0
	v_mov_b64_e32 v[108:109], 0
	v_mov_b64_e32 v[110:111], 0
	v_mov_b64_e32 v[116:117], 0
	v_mov_b64_e32 v[118:119], 0
	v_mov_b64_e32 v[88:89], 0
	v_mov_b64_e32 v[90:91], 0
	v_mov_b64_e32 v[96:97], 0
	v_mov_b64_e32 v[98:99], 0
	v_mov_b64_e32 v[104:105], 0
	v_mov_b64_e32 v[106:107], 0
	v_mov_b64_e32 v[112:113], 0
	v_mov_b64_e32 v[114:115], 0
	v_mov_b64_e32 v[120:121], 0
	v_mov_b64_e32 v[122:123], 0
	v_mov_b64_e32 v[124:125], 0
	v_mov_b64_e32 v[126:127], 0
	v_mov_b64_e32 v[128:129], 0
	v_mov_b64_e32 v[130:131], 0
	v_mov_b64_e32 v[132:133], 0
	v_mov_b64_e32 v[134:135], 0
	v_cmp_gt_i32_e32 vcc, 1, v174
	s_cbranch_vccz .LBB0_313
	s_branch .LBB0_327

.LBB0_327:
	s_add_i32 s8, s74, 2
	s_add_u32 s34, s30, 0xfff80080
	s_addc_u32 s35, s31, -1
	s_cmp_eq_u32 s71, s74
	s_cselect_b32 s37, s67, s35
	s_cselect_b32 s36, s68, s34
	s_cselect_b32 s35, s69, s73
	s_cselect_b32 s34, s70, s72
	s_cmpk_lt_i32 s3, 0x56
	s_cselect_b32 s74, s56, 0x2b00
	s_mov_b32 s75, 0xac00
	s_cselect_b32 s76, s75, 0x4000
	s_sub_i32 s74, s74, s33
	v_min3_i32 v5, s74, v174, 2
	v_sub_u32_e32 v174, v174, v5
	v_readfirstlane_b32 s78, v5
	s_max_i32 s74, s78, 0
	s_add_i32 s74, s33, s74
	s_add_i32 s77, s74, -1
	s_min_i32 s74, s33, s77
	s_mul_hi_i32 s75, s76, s74
	s_mul_i32 s74, s76, s74
	s_add_u32 s74, s38, s74
	s_addc_u32 s75, s39, s75
	s_mul_hi_i32 s79, s76, s77
	s_mul_i32 s76, s76, s77
	s_add_u32 s76, s38, s76
	global_load_dwordx4 v[152:155], v173, s[74:75] nt
	s_addc_u32 s77, s39, s79
	global_load_dwordx4 v[156:159], v173, s[76:77] nt
	s_add_i32 s33, s78, s33
	v_add_u32_e32 v5, s57, v177
	ds_read_b128 v[160:163], v5
	ds_read_b128 v[164:167], v5 offset:1024
	ds_read_b128 v[168:171], v5 offset:2048
	ds_read_b128 v[182:185], v5 offset:3072
	v_add_u32_e32 v5, s58, v177
	ds_read_b128 v[186:189], v5
	ds_read_b128 v[190:193], v5 offset:1024
	ds_read_b128 v[194:197], v5 offset:2048
	ds_read_b128 v[198:201], v5 offset:3072
	v_lshl_add_u64 v[6:7], s[30:31], 0, v[146:147]
	s_add_i32 m0, s46, 0xc000
	ds_read_b128 v[202:205], v180
	ds_read_b128 v[206:209], v180 offset:1024
	ds_read_b128 v[210:213], v180 offset:2048
	ds_read_b128 v[214:217], v180 offset:3072
	ds_read_b128 v[218:221], v180 offset:4096
	ds_read_b128 v[222:225], v180 offset:5120
	ds_read_b128 v[226:229], v180 offset:6144
	ds_read_b128 v[230:233], v180 offset:7168
	global_load_lds_dwordx4 v[6:7], off
	v_lshl_add_u64 v[6:7], s[30:31], 0, v[148:149]
	s_add_i32 m0, s46, 0xe000
	s_nop 0
	global_load_lds_dwordx4 v[6:7], off
	s_waitcnt vmcnt(10)
	s_waitcnt lgkmcnt(0)
	s_barrier
	s_setprio 1
	s_waitcnt lgkmcnt(0)
	v_mfma_i32_16x16x64_i8 v[132:135], v[160:163], v[202:205], v[132:135]
	v_mfma_i32_16x16x64_i8 v[128:131], v[168:171], v[202:205], v[128:131]
	v_mfma_i32_16x16x64_i8 v[124:127], v[160:163], v[210:213], v[124:127]
	v_mfma_i32_16x16x64_i8 v[120:123], v[168:171], v[210:213], v[120:123]
	v_mfma_i32_16x16x64_i8 v[112:115], v[160:163], v[218:221], v[112:115]
	v_mfma_i32_16x16x64_i8 v[104:107], v[168:171], v[218:221], v[104:107]
	v_mfma_i32_16x16x64_i8 v[96:99], v[160:163], v[226:229], v[96:99]
	v_mfma_i32_16x16x64_i8 v[88:91], v[168:171], v[226:229], v[88:91]
	v_mfma_i32_16x16x64_i8 v[132:135], v[164:167], v[206:209], v[132:135]
	v_mfma_i32_16x16x64_i8 v[128:131], v[182:185], v[206:209], v[128:131]
	v_mfma_i32_16x16x64_i8 v[124:127], v[164:167], v[214:217], v[124:127]
	v_mfma_i32_16x16x64_i8 v[120:123], v[182:185], v[214:217], v[120:123]
	v_mfma_i32_16x16x64_i8 v[112:115], v[164:167], v[222:225], v[112:115]
	v_mfma_i32_16x16x64_i8 v[104:107], v[182:185], v[222:225], v[104:107]
	v_mfma_i32_16x16x64_i8 v[96:99], v[164:167], v[230:233], v[96:99]
	v_mfma_i32_16x16x64_i8 v[88:91], v[182:185], v[230:233], v[88:91]
	s_setprio 0
	s_setprio 1
	v_mfma_i32_16x16x64_i8 v[116:119], v[186:189], v[202:205], v[116:119]
	v_mfma_i32_16x16x64_i8 v[108:111], v[194:197], v[202:205], v[108:111]
	v_mfma_i32_16x16x64_i8 v[100:103], v[186:189], v[210:213], v[100:103]
	v_mfma_i32_16x16x64_i8 v[92:95], v[194:197], v[210:213], v[92:95]
	v_mfma_i32_16x16x64_i8 v[84:87], v[186:189], v[218:221], v[84:87]
	v_mfma_i32_16x16x64_i8 v[80:83], v[194:197], v[218:221], v[80:83]
	v_mfma_i32_16x16x64_i8 v[76:79], v[186:189], v[226:229], v[76:79]
	v_mfma_i32_16x16x64_i8 v[72:75], v[194:197], v[226:229], v[72:75]
	v_mfma_i32_16x16x64_i8 v[116:119], v[190:193], v[206:209], v[116:119]
	v_mfma_i32_16x16x64_i8 v[108:111], v[198:201], v[206:209], v[108:111]
	v_mfma_i32_16x16x64_i8 v[100:103], v[190:193], v[214:217], v[100:103]
	v_mfma_i32_16x16x64_i8 v[92:95], v[198:201], v[214:217], v[92:95]
	v_mfma_i32_16x16x64_i8 v[84:87], v[190:193], v[222:225], v[84:87]
	v_mfma_i32_16x16x64_i8 v[80:83], v[198:201], v[222:225], v[80:83]
	v_mfma_i32_16x16x64_i8 v[76:79], v[190:193], v[230:233], v[76:79]
	v_mfma_i32_16x16x64_i8 v[72:75], v[198:201], v[230:233], v[72:75]
	s_setprio 0
	s_barrier
	s_add_i32 s74, s57, s45
	v_lshl_add_u64 v[236:237], s[34:35], 0, v[138:139]
	s_mov_b32 m0, s74
	ds_read_b128 v[202:205], v180 offset:16384
	ds_read_b128 v[206:209], v180 offset:17408
	ds_read_b128 v[210:213], v180 offset:18432
	ds_read_b128 v[214:217], v180 offset:19456
	ds_read_b128 v[218:221], v180 offset:20480
	ds_read_b128 v[222:225], v180 offset:21504
	ds_read_b128 v[226:229], v180 offset:22528
	ds_read_b128 v[230:233], v180 offset:23552
	global_load_lds_dwordx4 v[236:237], off
	s_add_i32 m0, s74, 0x2000
	s_add_u32 s74, s34, 0x80000
	v_lshl_add_u64 v[238:239], s[34:35], 0, v[142:143]
	s_addc_u32 s75, s35, 0
	s_add_i32 s76, s58, s45
	global_load_lds_dwordx4 v[238:239], off
	v_lshl_add_u64 v[6:7], s[74:75], 0, v[138:139]
	s_mov_b32 m0, s76
	v_lshl_add_u64 v[240:241], s[36:37], 0, v[136:137]
	global_load_lds_dwordx4 v[6:7], off
	v_lshl_add_u64 v[6:7], s[74:75], 0, v[142:143]
	s_add_i32 m0, s76, 0x2000
	v_lshl_add_u64 v[242:243], s[36:37], 0, v[140:141]
	global_load_lds_dwordx4 v[6:7], off
	s_mov_b32 m0, s46
	s_nop 0
	global_load_lds_dwordx4 v[240:241], off
	s_mov_b32 m0, s47
	s_nop 0
	global_load_lds_dwordx4 v[242:243], off
	s_waitcnt vmcnt(10)
	s_waitcnt lgkmcnt(0)
	s_barrier
	s_setprio 1
	s_waitcnt lgkmcnt(0)
	v_mfma_i32_16x16x64_i8 v[68:71], v[160:163], v[202:205], v[68:71]
	v_mfma_i32_16x16x64_i8 v[64:67], v[168:171], v[202:205], v[64:67]
	v_mfma_i32_16x16x64_i8 v[60:63], v[160:163], v[210:213], v[60:63]
	v_mfma_i32_16x16x64_i8 v[56:59], v[168:171], v[210:213], v[56:59]
	v_mfma_i32_16x16x64_i8 v[48:51], v[160:163], v[218:221], v[48:51]
	v_mfma_i32_16x16x64_i8 v[40:43], v[168:171], v[218:221], v[40:43]
	v_mfma_i32_16x16x64_i8 v[32:35], v[160:163], v[226:229], v[32:35]
	v_mfma_i32_16x16x64_i8 v[24:27], v[168:171], v[226:229], v[24:27]
	v_mfma_i32_16x16x64_i8 v[68:71], v[164:167], v[206:209], v[68:71]
	v_mfma_i32_16x16x64_i8 v[64:67], v[182:185], v[206:209], v[64:67]
	v_mfma_i32_16x16x64_i8 v[60:63], v[164:167], v[214:217], v[60:63]
	v_mfma_i32_16x16x64_i8 v[56:59], v[182:185], v[214:217], v[56:59]
	v_mfma_i32_16x16x64_i8 v[48:51], v[164:167], v[222:225], v[48:51]
	v_mfma_i32_16x16x64_i8 v[40:43], v[182:185], v[222:225], v[40:43]
	v_mfma_i32_16x16x64_i8 v[32:35], v[164:167], v[230:233], v[32:35]
	v_mfma_i32_16x16x64_i8 v[24:27], v[182:185], v[230:233], v[24:27]
	s_setprio 0
	s_setprio 1
	v_mfma_i32_16x16x64_i8 v[52:55], v[186:189], v[202:205], v[52:55]
	v_mfma_i32_16x16x64_i8 v[44:47], v[194:197], v[202:205], v[44:47]
	v_mfma_i32_16x16x64_i8 v[36:39], v[186:189], v[210:213], v[36:39]
	v_mfma_i32_16x16x64_i8 v[28:31], v[194:197], v[210:213], v[28:31]
	v_mfma_i32_16x16x64_i8 v[20:23], v[186:189], v[218:221], v[20:23]
	v_mfma_i32_16x16x64_i8 v[16:19], v[194:197], v[218:221], v[16:19]
	v_mfma_i32_16x16x64_i8 v[12:15], v[186:189], v[226:229], v[12:15]
	v_mfma_i32_16x16x64_i8 v[6:9], v[194:197], v[226:229], v[8:11]
	v_mfma_i32_16x16x64_i8 v[52:55], v[190:193], v[206:209], v[52:55]
	v_mfma_i32_16x16x64_i8 v[44:47], v[198:201], v[206:209], v[44:47]
	v_mfma_i32_16x16x64_i8 v[36:39], v[190:193], v[214:217], v[36:39]
	v_mfma_i32_16x16x64_i8 v[28:31], v[198:201], v[214:217], v[28:31]
	v_mfma_i32_16x16x64_i8 v[20:23], v[190:193], v[222:225], v[20:23]
	v_mfma_i32_16x16x64_i8 v[16:19], v[198:201], v[222:225], v[16:19]
	v_mfma_i32_16x16x64_i8 v[12:15], v[190:193], v[230:233], v[12:15]
	v_mfma_i32_16x16x64_i8 v[6:9], v[198:201], v[230:233], v[6:9]
	s_setprio 0
	s_barrier
	s_add_i32 s74, 0, 0x18000
	v_add_u32_e32 v5, s74, v177
	s_add_i32 s75, 0, 0x1c000
	ds_read_b128 v[160:163], v5
	ds_read_b128 v[164:167], v5 offset:1024
	ds_read_b128 v[168:171], v5 offset:2048
	ds_read_b128 v[182:185], v5 offset:3072
	v_add_u32_e32 v5, s75, v177
	ds_read_b128 v[186:189], v5
	ds_read_b128 v[190:193], v5 offset:1024
	ds_read_b128 v[194:197], v5 offset:2048
	ds_read_b128 v[198:201], v5 offset:3072
	s_add_u32 s36, s36, 0x80000
	s_addc_u32 s37, s37, 0
	s_mov_b32 m0, s48
	v_lshl_add_u64 v[10:11], s[36:37], 0, v[136:137]
	ds_read_b128 v[202:205], v180 offset:32768
	ds_read_b128 v[206:209], v180 offset:33792
	ds_read_b128 v[210:213], v180 offset:34816
	ds_read_b128 v[214:217], v180 offset:35840
	ds_read_b128 v[218:221], v180 offset:36864
	ds_read_b128 v[222:225], v180 offset:37888
	ds_read_b128 v[226:229], v180 offset:38912
	ds_read_b128 v[230:233], v180 offset:39936
	global_load_lds_dwordx4 v[10:11], off
	v_lshl_add_u64 v[10:11], s[36:37], 0, v[140:141]
	s_mov_b32 m0, s49
	s_nop 0
	global_load_lds_dwordx4 v[10:11], off
	s_waitcnt vmcnt(8)
	s_waitcnt lgkmcnt(0)
	s_barrier
	s_setprio 1
	s_waitcnt lgkmcnt(0)
	v_mfma_i32_16x16x64_i8 v[132:135], v[160:163], v[202:205], v[132:135]
	v_mfma_i32_16x16x64_i8 v[128:131], v[168:171], v[202:205], v[128:131]
	v_mfma_i32_16x16x64_i8 v[124:127], v[160:163], v[210:213], v[124:127]
	v_mfma_i32_16x16x64_i8 v[120:123], v[168:171], v[210:213], v[120:123]
	v_mfma_i32_16x16x64_i8 v[112:115], v[160:163], v[218:221], v[112:115]
	v_max3_f32 v0, v0, |v152|, |v156|
	v_mfma_i32_16x16x64_i8 v[104:107], v[168:171], v[218:221], v[104:107]
	v_max3_f32 v1, v1, |v153|, |v157|
	v_mfma_i32_16x16x64_i8 v[96:99], v[160:163], v[226:229], v[96:99]
	v_max3_f32 v2, v2, |v154|, |v158|
	v_mfma_i32_16x16x64_i8 v[88:91], v[168:171], v[226:229], v[88:91]
	v_max3_f32 v3, v3, |v155|, |v159|
	v_mfma_i32_16x16x64_i8 v[132:135], v[164:167], v[206:209], v[132:135]
	v_mfma_i32_16x16x64_i8 v[128:131], v[182:185], v[206:209], v[128:131]
	v_mfma_i32_16x16x64_i8 v[124:127], v[164:167], v[214:217], v[124:127]
	v_mfma_i32_16x16x64_i8 v[120:123], v[182:185], v[214:217], v[120:123]
	v_mfma_i32_16x16x64_i8 v[112:115], v[164:167], v[222:225], v[112:115]
	v_mfma_i32_16x16x64_i8 v[104:107], v[182:185], v[222:225], v[104:107]
	v_mfma_i32_16x16x64_i8 v[96:99], v[164:167], v[230:233], v[96:99]
	v_mfma_i32_16x16x64_i8 v[88:91], v[182:185], v[230:233], v[88:91]
	s_setprio 0
	s_setprio 1
	v_mfma_i32_16x16x64_i8 v[116:119], v[186:189], v[202:205], v[116:119]
	v_mfma_i32_16x16x64_i8 v[108:111], v[194:197], v[202:205], v[108:111]
	v_mfma_i32_16x16x64_i8 v[100:103], v[186:189], v[210:213], v[100:103]
	v_mfma_i32_16x16x64_i8 v[92:95], v[194:197], v[210:213], v[92:95]
	v_mfma_i32_16x16x64_i8 v[84:87], v[186:189], v[218:221], v[84:87]
	v_mfma_i32_16x16x64_i8 v[80:83], v[194:197], v[218:221], v[80:83]
	v_mfma_i32_16x16x64_i8 v[76:79], v[186:189], v[226:229], v[76:79]
	v_mfma_i32_16x16x64_i8 v[72:75], v[194:197], v[226:229], v[72:75]
	v_mfma_i32_16x16x64_i8 v[116:119], v[190:193], v[206:209], v[116:119]
	v_mfma_i32_16x16x64_i8 v[108:111], v[198:201], v[206:209], v[108:111]
	v_mfma_i32_16x16x64_i8 v[100:103], v[190:193], v[214:217], v[100:103]
	v_mfma_i32_16x16x64_i8 v[92:95], v[198:201], v[214:217], v[92:95]
	v_mfma_i32_16x16x64_i8 v[84:87], v[190:193], v[222:225], v[84:87]
	v_mfma_i32_16x16x64_i8 v[80:83], v[198:201], v[222:225], v[80:83]
	v_mfma_i32_16x16x64_i8 v[76:79], v[190:193], v[230:233], v[76:79]
	v_mfma_i32_16x16x64_i8 v[72:75], v[198:201], v[230:233], v[72:75]
	s_setprio 0
	s_barrier
	s_add_i32 s36, s74, s45
	v_lshl_add_u64 v[10:11], v[236:237], 0, s[14:15]
	s_mov_b32 m0, s36
	ds_read_b128 v[152:155], v180 offset:49152
	ds_read_b128 v[156:159], v180 offset:50176
	ds_read_b128 v[202:205], v180 offset:51200
	ds_read_b128 v[206:209], v180 offset:52224
	ds_read_b128 v[210:213], v180 offset:53248
	ds_read_b128 v[214:217], v180 offset:54272
	ds_read_b128 v[218:221], v180 offset:55296
	ds_read_b128 v[222:225], v180 offset:56320
	global_load_lds_dwordx4 v[10:11], off
	s_add_i32 m0, s36, 0x2000
	s_add_u32 s34, s34, 0x80080
	v_lshl_add_u64 v[10:11], v[238:239], 0, s[14:15]
	s_addc_u32 s35, s35, 0
	s_add_i32 s36, s75, s45
	global_load_lds_dwordx4 v[10:11], off
	v_lshl_add_u64 v[10:11], s[34:35], 0, v[138:139]
	s_mov_b32 m0, s36
	s_nop 0
	global_load_lds_dwordx4 v[10:11], off
	v_lshl_add_u64 v[10:11], s[34:35], 0, v[142:143]
	s_add_i32 m0, s36, 0x2000
	s_nop 0
	global_load_lds_dwordx4 v[10:11], off
	v_lshl_add_u64 v[10:11], v[240:241], 0, s[14:15]
	s_mov_b32 m0, s54
	s_nop 0
	global_load_lds_dwordx4 v[10:11], off
	v_lshl_add_u64 v[10:11], v[242:243], 0, s[14:15]
	s_mov_b32 m0, s55
	s_nop 0
	global_load_lds_dwordx4 v[10:11], off
	s_waitcnt vmcnt(8)
	s_waitcnt lgkmcnt(0)
	s_barrier
	s_setprio 1
	s_waitcnt lgkmcnt(0)
	v_mfma_i32_16x16x64_i8 v[68:71], v[160:163], v[152:155], v[68:71]
	v_mfma_i32_16x16x64_i8 v[64:67], v[168:171], v[152:155], v[64:67]
	v_mfma_i32_16x16x64_i8 v[60:63], v[160:163], v[202:205], v[60:63]
	v_mfma_i32_16x16x64_i8 v[56:59], v[168:171], v[202:205], v[56:59]
	v_mfma_i32_16x16x64_i8 v[48:51], v[160:163], v[210:213], v[48:51]
	v_mfma_i32_16x16x64_i8 v[40:43], v[168:171], v[210:213], v[40:43]
	v_mfma_i32_16x16x64_i8 v[32:35], v[160:163], v[218:221], v[32:35]
	v_mfma_i32_16x16x64_i8 v[24:27], v[168:171], v[218:221], v[24:27]
	v_mfma_i32_16x16x64_i8 v[68:71], v[164:167], v[156:159], v[68:71]
	v_mfma_i32_16x16x64_i8 v[64:67], v[182:185], v[156:159], v[64:67]
	v_mfma_i32_16x16x64_i8 v[60:63], v[164:167], v[206:209], v[60:63]
	v_mfma_i32_16x16x64_i8 v[56:59], v[182:185], v[206:209], v[56:59]
	v_mfma_i32_16x16x64_i8 v[48:51], v[164:167], v[214:217], v[48:51]
	v_mfma_i32_16x16x64_i8 v[40:43], v[182:185], v[214:217], v[40:43]
	v_mfma_i32_16x16x64_i8 v[32:35], v[164:167], v[222:225], v[32:35]
	v_mfma_i32_16x16x64_i8 v[24:27], v[182:185], v[222:225], v[24:27]
	s_setprio 0
	s_setprio 1
	v_mfma_i32_16x16x64_i8 v[52:55], v[186:189], v[152:155], v[52:55]
	v_mfma_i32_16x16x64_i8 v[44:47], v[194:197], v[152:155], v[44:47]
	v_mfma_i32_16x16x64_i8 v[36:39], v[186:189], v[202:205], v[36:39]
	v_mfma_i32_16x16x64_i8 v[28:31], v[194:197], v[202:205], v[28:31]
	v_mfma_i32_16x16x64_i8 v[20:23], v[186:189], v[210:213], v[20:23]
	v_mfma_i32_16x16x64_i8 v[16:19], v[194:197], v[210:213], v[16:19]
	v_mfma_i32_16x16x64_i8 v[10:13], v[186:189], v[218:221], v[12:15]
	v_mfma_i32_16x16x64_i8 v[6:9], v[194:197], v[218:221], v[6:9]
	v_mfma_i32_16x16x64_i8 v[52:55], v[190:193], v[156:159], v[52:55]
	v_mfma_i32_16x16x64_i8 v[44:47], v[198:201], v[156:159], v[44:47]
	v_mfma_i32_16x16x64_i8 v[36:39], v[190:193], v[206:209], v[36:39]
	v_mfma_i32_16x16x64_i8 v[28:31], v[198:201], v[206:209], v[28:31]
	v_mfma_i32_16x16x64_i8 v[20:23], v[190:193], v[214:217], v[20:23]
	v_mfma_i32_16x16x64_i8 v[16:19], v[198:201], v[214:217], v[16:19]
	v_mfma_i32_16x16x64_i8 v[12:15], v[190:193], v[222:225], v[10:13]
	v_mfma_i32_16x16x64_i8 v[8:11], v[198:201], v[222:225], v[6:9]
	s_setprio 0
	s_barrier
	s_add_u32 s30, s30, 0x100
	s_addc_u32 s31, s31, 0
	s_add_u32 s72, s72, 0x100
	s_addc_u32 s73, s73, 0
	s_cmp_ge_i32 s8, s66
	s_cbranch_scc0 .LBB0_312
	v_cvt_f32_i32_e32 v154, v132
	v_cvt_f32_i32_e32 v155, v133
	v_cvt_f32_i32_e32 v152, v134
	v_cvt_f32_i32_e32 v153, v135
	v_cvt_f32_i32_e32 v132, v128
	v_cvt_f32_i32_e32 v133, v129
	v_cvt_f32_i32_e32 v134, v130
	v_cvt_f32_i32_e32 v135, v131
	v_cvt_f32_i32_e32 v158, v116
	v_cvt_f32_i32_e32 v159, v117
	v_cvt_f32_i32_e32 v162, v118
	v_cvt_f32_i32_e32 v163, v119
	v_cvt_f32_i32_e32 v156, v108
	v_cvt_f32_i32_e32 v157, v109
	v_cvt_f32_i32_e32 v160, v110
	v_cvt_f32_i32_e32 v161, v111
	v_cvt_f32_i32_e32 v116, v124
	v_cvt_f32_i32_e32 v117, v125
	v_cvt_f32_i32_e32 v118, v126
	v_cvt_f32_i32_e32 v119, v127
	v_cvt_f32_i32_e32 v120, v120
	v_cvt_f32_i32_e32 v121, v121
	v_cvt_f32_i32_e32 v122, v122
	v_cvt_f32_i32_e32 v123, v123
	v_cvt_f32_i32_e32 v124, v100
	v_cvt_f32_i32_e32 v125, v101
	v_cvt_f32_i32_e32 v126, v102
	v_cvt_f32_i32_e32 v127, v103
	v_cvt_f32_i32_e32 v128, v92
	v_cvt_f32_i32_e32 v129, v93
	v_cvt_f32_i32_e32 v130, v94
	v_cvt_f32_i32_e32 v131, v95
	v_cvt_f32_i32_e32 v112, v112
	v_cvt_f32_i32_e32 v113, v113
	v_cvt_f32_i32_e32 v114, v114
	v_cvt_f32_i32_e32 v115, v115
	v_cvt_f32_i32_e32 v100, v104
	v_cvt_f32_i32_e32 v101, v105
	v_cvt_f32_i32_e32 v102, v106
	v_cvt_f32_i32_e32 v103, v107
	v_cvt_f32_i32_e32 v104, v84
	v_cvt_f32_i32_e32 v105, v85
	v_cvt_f32_i32_e32 v106, v86
	v_cvt_f32_i32_e32 v107, v87
	v_cvt_f32_i32_e32 v108, v80
	v_cvt_f32_i32_e32 v109, v81
	v_cvt_f32_i32_e32 v110, v82
	v_cvt_f32_i32_e32 v111, v83
	v_cvt_f32_i32_e32 v80, v96
	v_cvt_f32_i32_e32 v81, v97
	v_cvt_f32_i32_e32 v82, v98
	v_cvt_f32_i32_e32 v83, v99
	v_cvt_f32_i32_e32 v84, v88
	v_cvt_f32_i32_e32 v85, v89
	v_cvt_f32_i32_e32 v86, v90
	v_cvt_f32_i32_e32 v87, v91
	v_cvt_f32_i32_e32 v90, v76
	v_cvt_f32_i32_e32 v91, v77
	v_cvt_f32_i32_e32 v92, v78
	v_cvt_f32_i32_e32 v93, v79
	v_cvt_f32_i32_e32 v94, v72
	v_cvt_f32_i32_e32 v95, v73
	v_cvt_f32_i32_e32 v96, v74
	v_cvt_f32_i32_e32 v97, v75
	v_cvt_f32_i32_e32 v68, v68
	v_cvt_f32_i32_e32 v69, v69
	v_cvt_f32_i32_e32 v70, v70
	v_cvt_f32_i32_e32 v71, v71
	v_cvt_f32_i32_e32 v72, v64
	v_cvt_f32_i32_e32 v73, v65
	v_cvt_f32_i32_e32 v66, v66
	v_cvt_f32_i32_e32 v67, v67
	v_cvt_f32_i32_e32 v74, v52
	v_cvt_f32_i32_e32 v75, v53
	v_cvt_f32_i32_e32 v76, v54
	v_cvt_f32_i32_e32 v77, v55
	v_cvt_f32_i32_e32 v78, v44
	v_cvt_f32_i32_e32 v79, v45
	v_cvt_f32_i32_e32 v88, v46
	v_cvt_f32_i32_e32 v89, v47
	v_cvt_f32_i32_e32 v46, v60
	v_cvt_f32_i32_e32 v47, v61
	v_cvt_f32_i32_e32 v52, v62
	v_cvt_f32_i32_e32 v53, v63
	v_cvt_f32_i32_e32 v54, v56
	v_cvt_f32_i32_e32 v55, v57
	v_cvt_f32_i32_e32 v56, v58
	v_cvt_f32_i32_e32 v57, v59
	v_cvt_f32_i32_e32 v58, v36
	v_cvt_f32_i32_e32 v59, v37
	v_cvt_f32_i32_e32 v60, v38
	v_cvt_f32_i32_e32 v61, v39
	v_cvt_f32_i32_e32 v62, v28
	v_cvt_f32_i32_e32 v63, v29
	v_cvt_f32_i32_e32 v64, v30
	v_cvt_f32_i32_e32 v65, v31
	v_cvt_f32_i32_e32 v28, v48
	v_cvt_f32_i32_e32 v29, v49
	v_cvt_f32_i32_e32 v30, v50
	v_cvt_f32_i32_e32 v31, v51
	v_cvt_f32_i32_e32 v36, v40
	v_cvt_f32_i32_e32 v37, v41
	v_cvt_f32_i32_e32 v38, v42
	v_cvt_f32_i32_e32 v39, v43
	v_cvt_f32_i32_e32 v40, v20
	v_cvt_f32_i32_e32 v41, v21
	v_cvt_f32_i32_e32 v22, v22
	v_cvt_f32_i32_e32 v23, v23
	v_cvt_f32_i32_e32 v42, v16
	v_cvt_f32_i32_e32 v43, v17
	v_cvt_f32_i32_e32 v44, v18
	v_cvt_f32_i32_e32 v45, v19
	v_cvt_f32_i32_e32 v6, v32
	v_cvt_f32_i32_e32 v7, v33
	v_cvt_f32_i32_e32 v16, v34
	v_cvt_f32_i32_e32 v17, v35
	v_cvt_f32_i32_e32 v18, v24
	v_cvt_f32_i32_e32 v19, v25
	v_cvt_f32_i32_e32 v20, v26
	v_cvt_f32_i32_e32 v21, v27
	v_cvt_f32_i32_e32 v12, v12
	v_cvt_f32_i32_e32 v13, v13
	v_cvt_f32_i32_e32 v14, v14
	v_cvt_f32_i32_e32 v15, v15
	v_cvt_f32_i32_e32 v8, v8
	v_cvt_f32_i32_e32 v9, v9
	v_cvt_f32_i32_e32 v10, v10
	v_cvt_f32_i32_e32 v11, v11
	s_and_b64 vcc, exec, s[16:17]
	s_cbranch_vccz .LBB0_330

.LBB0_1033:
	s_add_i32 s8, s71, 2
	s_add_u32 s28, s26, 0xfff00080
	s_addc_u32 s29, s27, -1
	s_cmp_eq_u32 s68, s71
	s_cselect_b32 s31, s64, s29
	s_cselect_b32 s30, s65, s28
	s_cselect_b32 s29, s66, s70
	s_cselect_b32 s28, s67, s69
	s_cmpk_lt_i32 s3, 0x56
	s_cselect_b32 s71, s52, 0x2b00
	s_mov_b32 s72, 0xac00
	s_cselect_b32 s74, s72, 0x4000
	s_sub_i32 s71, s71, s33
	v_min3_i32 v5, s71, v160, 2
	v_sub_u32_e32 v160, v160, v5
	v_readfirstlane_b32 s71, v5
	s_max_i32 s72, s71, 0
	s_add_i32 s72, s33, s72
	s_add_i32 s75, s72, -1
	s_min_i32 s72, s33, s75
	s_mul_hi_i32 s73, s74, s72
	s_mul_i32 s72, s74, s72
	s_add_u32 s72, s34, s72
	s_addc_u32 s73, s35, s73
	s_mul_hi_i32 s76, s74, s75
	s_mul_i32 s74, s74, s75
	s_add_u32 s74, s34, s74
	global_load_dwordx4 v[152:155], v159, s[72:73] nt
	s_addc_u32 s75, s35, s76
	global_load_dwordx4 v[168:171], v159, s[74:75] nt
	s_add_i32 s33, s71, s33
	v_add_u32_e32 v5, s53, v163
	ds_read_b128 v[172:175], v5
	ds_read_b128 v[176:179], v5 offset:1024
	ds_read_b128 v[180:183], v5 offset:2048
	ds_read_b128 v[184:187], v5 offset:3072
	v_add_u32_e32 v5, s54, v163
	ds_read_b128 v[188:191], v5
	ds_read_b128 v[192:195], v5 offset:1024
	ds_read_b128 v[196:199], v5 offset:2048
	ds_read_b128 v[200:203], v5 offset:3072
	v_lshl_add_u64 v[6:7], s[26:27], 0, v[146:147]
	s_add_i32 m0, s43, 0xc000
	ds_read_b128 v[204:207], v166
	ds_read_b128 v[208:211], v166 offset:1024
	ds_read_b128 v[212:215], v166 offset:2048
	ds_read_b128 v[216:219], v166 offset:3072
	ds_read_b128 v[220:223], v166 offset:4096
	ds_read_b128 v[224:227], v166 offset:5120
	ds_read_b128 v[236:239], v166 offset:6144
	ds_read_b128 v[240:243], v166 offset:7168
	global_load_lds_dwordx4 v[6:7], off
	v_lshl_add_u64 v[6:7], s[26:27], 0, v[148:149]
	s_add_i32 m0, s43, 0xe000
	s_nop 0
	global_load_lds_dwordx4 v[6:7], off
	s_waitcnt vmcnt(10)
	s_waitcnt lgkmcnt(0)
	s_barrier
	s_setprio 1
	s_waitcnt lgkmcnt(0)
	v_mfma_f32_16x16x32_bf16 v[132:135], v[172:175], v[204:207], v[132:135]
	v_mfma_f32_16x16x32_bf16 v[128:131], v[180:183], v[204:207], v[128:131]
	v_mfma_f32_16x16x32_bf16 v[116:119], v[172:175], v[212:215], v[116:119]
	v_mfma_f32_16x16x32_bf16 v[112:115], v[180:183], v[212:215], v[112:115]
	v_mfma_f32_16x16x32_bf16 v[100:103], v[172:175], v[220:223], v[100:103]
	v_mfma_f32_16x16x32_bf16 v[96:99], v[180:183], v[220:223], v[96:99]
	v_mfma_f32_16x16x32_bf16 v[84:87], v[172:175], v[236:239], v[84:87]
	v_mfma_f32_16x16x32_bf16 v[80:83], v[180:183], v[236:239], v[80:83]
	v_mfma_f32_16x16x32_bf16 v[132:135], v[176:179], v[208:211], v[132:135]
	v_mfma_f32_16x16x32_bf16 v[128:131], v[184:187], v[208:211], v[128:131]
	v_mfma_f32_16x16x32_bf16 v[116:119], v[176:179], v[216:219], v[116:119]
	v_mfma_f32_16x16x32_bf16 v[112:115], v[184:187], v[216:219], v[112:115]
	v_mfma_f32_16x16x32_bf16 v[100:103], v[176:179], v[224:227], v[100:103]
	v_mfma_f32_16x16x32_bf16 v[96:99], v[184:187], v[224:227], v[96:99]
	v_mfma_f32_16x16x32_bf16 v[84:87], v[176:179], v[240:243], v[84:87]
	v_mfma_f32_16x16x32_bf16 v[80:83], v[184:187], v[240:243], v[80:83]
	s_setprio 0
	s_setprio 1
	v_mfma_f32_16x16x32_bf16 v[124:127], v[188:191], v[204:207], v[124:127]
	v_mfma_f32_16x16x32_bf16 v[120:123], v[196:199], v[204:207], v[120:123]
	v_mfma_f32_16x16x32_bf16 v[108:111], v[188:191], v[212:215], v[108:111]
	v_mfma_f32_16x16x32_bf16 v[104:107], v[196:199], v[212:215], v[104:107]
	v_mfma_f32_16x16x32_bf16 v[92:95], v[188:191], v[220:223], v[92:95]
	v_mfma_f32_16x16x32_bf16 v[88:91], v[196:199], v[220:223], v[88:91]
	v_mfma_f32_16x16x32_bf16 v[76:79], v[188:191], v[236:239], v[76:79]
	v_mfma_f32_16x16x32_bf16 v[72:75], v[196:199], v[236:239], v[72:75]
	v_mfma_f32_16x16x32_bf16 v[124:127], v[192:195], v[208:211], v[124:127]
	v_mfma_f32_16x16x32_bf16 v[120:123], v[200:203], v[208:211], v[120:123]
	v_mfma_f32_16x16x32_bf16 v[108:111], v[192:195], v[216:219], v[108:111]
	v_mfma_f32_16x16x32_bf16 v[104:107], v[200:203], v[216:219], v[104:107]
	v_mfma_f32_16x16x32_bf16 v[92:95], v[192:195], v[224:227], v[92:95]
	v_mfma_f32_16x16x32_bf16 v[88:91], v[200:203], v[224:227], v[88:91]
	v_mfma_f32_16x16x32_bf16 v[76:79], v[192:195], v[240:243], v[76:79]
	v_mfma_f32_16x16x32_bf16 v[72:75], v[200:203], v[240:243], v[72:75]
	s_setprio 0
	s_barrier
	s_add_i32 s71, s53, s40
	v_lshl_add_u64 v[156:157], s[28:29], 0, v[138:139]
	s_mov_b32 m0, s71
	ds_read_b128 v[204:207], v166 offset:16384
	ds_read_b128 v[208:211], v166 offset:17408
	ds_read_b128 v[212:215], v166 offset:18432
	ds_read_b128 v[216:219], v166 offset:19456
	ds_read_b128 v[220:223], v166 offset:20480
	ds_read_b128 v[224:227], v166 offset:21504
	ds_read_b128 v[236:239], v166 offset:22528
	ds_read_b128 v[240:243], v166 offset:23552
	global_load_lds_dwordx4 v[156:157], off
	s_add_i32 m0, s71, 0x2000
	s_add_u32 s72, s28, 0x100000
	v_lshl_add_u64 v[244:245], s[28:29], 0, v[142:143]
	s_addc_u32 s73, s29, 0
	s_add_i32 s71, s54, s40
	global_load_lds_dwordx4 v[244:245], off
	v_lshl_add_u64 v[6:7], s[72:73], 0, v[138:139]
	s_mov_b32 m0, s71
	v_lshl_add_u64 v[246:247], s[30:31], 0, v[136:137]
	global_load_lds_dwordx4 v[6:7], off
	v_lshl_add_u64 v[6:7], s[72:73], 0, v[142:143]
	s_add_i32 m0, s71, 0x2000
	v_lshl_add_u64 v[248:249], s[30:31], 0, v[140:141]
	global_load_lds_dwordx4 v[6:7], off
	s_mov_b32 m0, s43
	s_nop 0
	global_load_lds_dwordx4 v[246:247], off
	s_mov_b32 m0, s44
	s_nop 0
	global_load_lds_dwordx4 v[248:249], off
	s_waitcnt vmcnt(10)
	s_waitcnt lgkmcnt(0)
	s_barrier
	s_setprio 1
	s_waitcnt lgkmcnt(0)
	v_mfma_f32_16x16x32_bf16 v[68:71], v[172:175], v[204:207], v[68:71]
	v_mfma_f32_16x16x32_bf16 v[64:67], v[180:183], v[204:207], v[64:67]
	v_mfma_f32_16x16x32_bf16 v[52:55], v[172:175], v[212:215], v[52:55]
	v_mfma_f32_16x16x32_bf16 v[48:51], v[180:183], v[212:215], v[48:51]
	v_mfma_f32_16x16x32_bf16 v[36:39], v[172:175], v[220:223], v[36:39]
	v_mfma_f32_16x16x32_bf16 v[32:35], v[180:183], v[220:223], v[32:35]
	v_mfma_f32_16x16x32_bf16 v[20:23], v[172:175], v[236:239], v[20:23]
	v_mfma_f32_16x16x32_bf16 v[16:19], v[180:183], v[236:239], v[16:19]
	v_mfma_f32_16x16x32_bf16 v[68:71], v[176:179], v[208:211], v[68:71]
	v_mfma_f32_16x16x32_bf16 v[64:67], v[184:187], v[208:211], v[64:67]
	v_mfma_f32_16x16x32_bf16 v[52:55], v[176:179], v[216:219], v[52:55]
	v_mfma_f32_16x16x32_bf16 v[48:51], v[184:187], v[216:219], v[48:51]
	v_mfma_f32_16x16x32_bf16 v[36:39], v[176:179], v[224:227], v[36:39]
	v_mfma_f32_16x16x32_bf16 v[32:35], v[184:187], v[224:227], v[32:35]
	v_mfma_f32_16x16x32_bf16 v[20:23], v[176:179], v[240:243], v[20:23]
	v_mfma_f32_16x16x32_bf16 v[16:19], v[184:187], v[240:243], v[16:19]
	s_setprio 0
	s_setprio 1
	v_mfma_f32_16x16x32_bf16 v[60:63], v[188:191], v[204:207], v[60:63]
	v_mfma_f32_16x16x32_bf16 v[56:59], v[196:199], v[204:207], v[56:59]
	v_mfma_f32_16x16x32_bf16 v[44:47], v[188:191], v[212:215], v[44:47]
	v_mfma_f32_16x16x32_bf16 v[40:43], v[196:199], v[212:215], v[40:43]
	v_mfma_f32_16x16x32_bf16 v[28:31], v[188:191], v[220:223], v[28:31]
	v_mfma_f32_16x16x32_bf16 v[24:27], v[196:199], v[220:223], v[24:27]
	v_mfma_f32_16x16x32_bf16 v[12:15], v[188:191], v[236:239], v[12:15]
	v_mfma_f32_16x16x32_bf16 v[6:9], v[196:199], v[236:239], v[8:11]
	v_mfma_f32_16x16x32_bf16 v[60:63], v[192:195], v[208:211], v[60:63]
	v_mfma_f32_16x16x32_bf16 v[56:59], v[200:203], v[208:211], v[56:59]
	v_mfma_f32_16x16x32_bf16 v[44:47], v[192:195], v[216:219], v[44:47]
	v_mfma_f32_16x16x32_bf16 v[40:43], v[200:203], v[216:219], v[40:43]
	v_mfma_f32_16x16x32_bf16 v[28:31], v[192:195], v[224:227], v[28:31]
	v_mfma_f32_16x16x32_bf16 v[24:27], v[200:203], v[224:227], v[24:27]
	v_mfma_f32_16x16x32_bf16 v[12:15], v[192:195], v[240:243], v[12:15]
	v_mfma_f32_16x16x32_bf16 v[6:9], v[200:203], v[240:243], v[6:9]
	s_setprio 0
	s_barrier
	s_add_i32 s71, 0, 0x18000
	v_add_u32_e32 v5, s71, v163
	s_add_i32 s72, 0, 0x1c000
	ds_read_b128 v[172:175], v5
	ds_read_b128 v[176:179], v5 offset:1024
	ds_read_b128 v[180:183], v5 offset:2048
	ds_read_b128 v[184:187], v5 offset:3072
	v_add_u32_e32 v5, s72, v163
	ds_read_b128 v[188:191], v5
	ds_read_b128 v[192:195], v5 offset:1024
	ds_read_b128 v[196:199], v5 offset:2048
	ds_read_b128 v[200:203], v5 offset:3072
	s_add_u32 s30, s30, 0x100000
	s_addc_u32 s31, s31, 0
	s_mov_b32 m0, s45
	v_lshl_add_u64 v[10:11], s[30:31], 0, v[136:137]
	ds_read_b128 v[204:207], v166 offset:32768
	ds_read_b128 v[208:211], v166 offset:33792
	ds_read_b128 v[212:215], v166 offset:34816
	ds_read_b128 v[216:219], v166 offset:35840
	ds_read_b128 v[220:223], v166 offset:36864
	ds_read_b128 v[224:227], v166 offset:37888
	ds_read_b128 v[236:239], v166 offset:38912
	ds_read_b128 v[240:243], v166 offset:39936
	global_load_lds_dwordx4 v[10:11], off
	v_lshl_add_u64 v[10:11], s[30:31], 0, v[140:141]
	s_mov_b32 m0, s46
	s_nop 0
	global_load_lds_dwordx4 v[10:11], off
	s_waitcnt vmcnt(8)
	s_waitcnt lgkmcnt(0)
	s_barrier
	s_setprio 1
	s_waitcnt lgkmcnt(0)
	v_mfma_f32_16x16x32_bf16 v[132:135], v[172:175], v[204:207], v[132:135]
	v_mfma_f32_16x16x32_bf16 v[128:131], v[180:183], v[204:207], v[128:131]
	v_mfma_f32_16x16x32_bf16 v[116:119], v[172:175], v[212:215], v[116:119]
	v_mfma_f32_16x16x32_bf16 v[112:115], v[180:183], v[212:215], v[112:115]
	v_mfma_f32_16x16x32_bf16 v[100:103], v[172:175], v[220:223], v[100:103]
	v_max3_f32 v0, v0, |v152|, |v168|
	v_mfma_f32_16x16x32_bf16 v[96:99], v[180:183], v[220:223], v[96:99]
	v_max3_f32 v1, v1, |v153|, |v169|
	v_mfma_f32_16x16x32_bf16 v[84:87], v[172:175], v[236:239], v[84:87]
	v_max3_f32 v2, v2, |v154|, |v170|
	v_mfma_f32_16x16x32_bf16 v[80:83], v[180:183], v[236:239], v[80:83]
	v_max3_f32 v3, v3, |v155|, |v171|
	v_mfma_f32_16x16x32_bf16 v[132:135], v[176:179], v[208:211], v[132:135]
	v_mfma_f32_16x16x32_bf16 v[128:131], v[184:187], v[208:211], v[128:131]
	v_mfma_f32_16x16x32_bf16 v[116:119], v[176:179], v[216:219], v[116:119]
	v_mfma_f32_16x16x32_bf16 v[112:115], v[184:187], v[216:219], v[112:115]
	v_mfma_f32_16x16x32_bf16 v[100:103], v[176:179], v[224:227], v[100:103]
	v_mfma_f32_16x16x32_bf16 v[96:99], v[184:187], v[224:227], v[96:99]
	v_mfma_f32_16x16x32_bf16 v[84:87], v[176:179], v[240:243], v[84:87]
	v_mfma_f32_16x16x32_bf16 v[80:83], v[184:187], v[240:243], v[80:83]
	s_setprio 0
	s_setprio 1
	v_mfma_f32_16x16x32_bf16 v[124:127], v[188:191], v[204:207], v[124:127]
	v_mfma_f32_16x16x32_bf16 v[120:123], v[196:199], v[204:207], v[120:123]
	v_mfma_f32_16x16x32_bf16 v[108:111], v[188:191], v[212:215], v[108:111]
	v_mfma_f32_16x16x32_bf16 v[104:107], v[196:199], v[212:215], v[104:107]
	v_mfma_f32_16x16x32_bf16 v[92:95], v[188:191], v[220:223], v[92:95]
	v_mfma_f32_16x16x32_bf16 v[88:91], v[196:199], v[220:223], v[88:91]
	v_mfma_f32_16x16x32_bf16 v[76:79], v[188:191], v[236:239], v[76:79]
	v_mfma_f32_16x16x32_bf16 v[72:75], v[196:199], v[236:239], v[72:75]
	v_mfma_f32_16x16x32_bf16 v[124:127], v[192:195], v[208:211], v[124:127]
	v_mfma_f32_16x16x32_bf16 v[120:123], v[200:203], v[208:211], v[120:123]
	v_mfma_f32_16x16x32_bf16 v[108:111], v[192:195], v[216:219], v[108:111]
	v_mfma_f32_16x16x32_bf16 v[104:107], v[200:203], v[216:219], v[104:107]
	v_mfma_f32_16x16x32_bf16 v[92:95], v[192:195], v[224:227], v[92:95]
	v_mfma_f32_16x16x32_bf16 v[88:91], v[200:203], v[224:227], v[88:91]
	v_mfma_f32_16x16x32_bf16 v[76:79], v[192:195], v[240:243], v[76:79]
	v_mfma_f32_16x16x32_bf16 v[72:75], v[200:203], v[240:243], v[72:75]
	s_setprio 0
	s_barrier
	s_add_i32 s30, s71, s40
	v_lshl_add_u64 v[10:11], v[156:157], 0, s[6:7]
	s_mov_b32 m0, s30
	ds_read_b128 v[152:155], v166 offset:49152
	ds_read_b128 v[168:171], v166 offset:50176
	ds_read_b128 v[204:207], v166 offset:51200
	ds_read_b128 v[208:211], v166 offset:52224
	ds_read_b128 v[212:215], v166 offset:53248
	ds_read_b128 v[216:219], v166 offset:54272
	ds_read_b128 v[220:223], v166 offset:55296
	ds_read_b128 v[224:227], v166 offset:56320
	global_load_lds_dwordx4 v[10:11], off
	s_add_i32 m0, s30, 0x2000
	s_add_u32 s28, s28, 0x100080
	v_lshl_add_u64 v[10:11], v[244:245], 0, s[6:7]
	s_addc_u32 s29, s29, 0
	s_add_i32 s30, s72, s40
	global_load_lds_dwordx4 v[10:11], off
	v_lshl_add_u64 v[10:11], s[28:29], 0, v[138:139]
	s_mov_b32 m0, s30
	s_nop 0
	global_load_lds_dwordx4 v[10:11], off
	v_lshl_add_u64 v[10:11], s[28:29], 0, v[142:143]
	s_add_i32 m0, s30, 0x2000
	s_nop 0
	global_load_lds_dwordx4 v[10:11], off
	v_lshl_add_u64 v[10:11], v[246:247], 0, s[6:7]
	s_mov_b32 m0, s49
	s_nop 0
	global_load_lds_dwordx4 v[10:11], off
	v_lshl_add_u64 v[10:11], v[248:249], 0, s[6:7]
	s_mov_b32 m0, s50
	s_nop 0
	global_load_lds_dwordx4 v[10:11], off
	s_waitcnt vmcnt(8)
	s_waitcnt lgkmcnt(0)
	s_barrier
	s_setprio 1
	s_waitcnt lgkmcnt(0)
	v_mfma_f32_16x16x32_bf16 v[68:71], v[172:175], v[152:155], v[68:71]
	v_mfma_f32_16x16x32_bf16 v[64:67], v[180:183], v[152:155], v[64:67]
	v_mfma_f32_16x16x32_bf16 v[52:55], v[172:175], v[204:207], v[52:55]
	v_mfma_f32_16x16x32_bf16 v[48:51], v[180:183], v[204:207], v[48:51]
	v_mfma_f32_16x16x32_bf16 v[36:39], v[172:175], v[212:215], v[36:39]
	v_mfma_f32_16x16x32_bf16 v[32:35], v[180:183], v[212:215], v[32:35]
	v_mfma_f32_16x16x32_bf16 v[20:23], v[172:175], v[220:223], v[20:23]
	v_mfma_f32_16x16x32_bf16 v[16:19], v[180:183], v[220:223], v[16:19]
	v_mfma_f32_16x16x32_bf16 v[68:71], v[176:179], v[168:171], v[68:71]
	v_mfma_f32_16x16x32_bf16 v[64:67], v[184:187], v[168:171], v[64:67]
	v_mfma_f32_16x16x32_bf16 v[52:55], v[176:179], v[208:211], v[52:55]
	v_mfma_f32_16x16x32_bf16 v[48:51], v[184:187], v[208:211], v[48:51]
	v_mfma_f32_16x16x32_bf16 v[36:39], v[176:179], v[216:219], v[36:39]
	v_mfma_f32_16x16x32_bf16 v[32:35], v[184:187], v[216:219], v[32:35]
	v_mfma_f32_16x16x32_bf16 v[20:23], v[176:179], v[224:227], v[20:23]
	v_mfma_f32_16x16x32_bf16 v[16:19], v[184:187], v[224:227], v[16:19]
	s_setprio 0
	s_setprio 1
	v_mfma_f32_16x16x32_bf16 v[60:63], v[188:191], v[152:155], v[60:63]
	v_mfma_f32_16x16x32_bf16 v[56:59], v[196:199], v[152:155], v[56:59]
	v_mfma_f32_16x16x32_bf16 v[44:47], v[188:191], v[204:207], v[44:47]
	v_mfma_f32_16x16x32_bf16 v[40:43], v[196:199], v[204:207], v[40:43]
	v_mfma_f32_16x16x32_bf16 v[28:31], v[188:191], v[212:215], v[28:31]
	v_mfma_f32_16x16x32_bf16 v[24:27], v[196:199], v[212:215], v[24:27]
	v_mfma_f32_16x16x32_bf16 v[10:13], v[188:191], v[220:223], v[12:15]
	v_mfma_f32_16x16x32_bf16 v[6:9], v[196:199], v[220:223], v[6:9]
	v_mfma_f32_16x16x32_bf16 v[60:63], v[192:195], v[168:171], v[60:63]
	v_mfma_f32_16x16x32_bf16 v[56:59], v[200:203], v[168:171], v[56:59]
	v_mfma_f32_16x16x32_bf16 v[44:47], v[192:195], v[208:211], v[44:47]
	v_mfma_f32_16x16x32_bf16 v[40:43], v[200:203], v[208:211], v[40:43]
	v_mfma_f32_16x16x32_bf16 v[28:31], v[192:195], v[216:219], v[28:31]
	v_mfma_f32_16x16x32_bf16 v[24:27], v[200:203], v[216:219], v[24:27]
	v_mfma_f32_16x16x32_bf16 v[12:15], v[192:195], v[224:227], v[10:13]
	v_mfma_f32_16x16x32_bf16 v[8:11], v[200:203], v[224:227], v[6:9]
	s_setprio 0
	s_barrier
	s_add_u32 s26, s26, 0x100
	s_addc_u32 s27, s27, 0
	s_add_u32 s69, s69, 0x100
	s_addc_u32 s70, s70, 0
	s_cmp_ge_i32 s8, s63
	s_cbranch_scc0 .LBB0_1018
	v_readlane_b32 s64, v254, 26
	v_readlane_b32 s65, v254, 27
	s_and_b64 vcc, exec, s[10:11]
	s_cbranch_vccz .LBB0_1036

.LBB0_1236:
	s_lshl_b32 s8, s64, 20
	s_and_b32 s8, s8, 0xff00000
	s_add_u32 s8, s43, s8
	s_addc_u32 s29, s44, 0
	s_lshl_b32 s28, s65, 7
	s_and_b32 s34, s28, 0x7fff80
	s_add_u32 s28, s8, s34
	s_addc_u32 s29, s29, 0
	s_lshl_b32 s8, s64, 12
	s_and_b32 s8, s8, 0xff00000
	v_readlane_b32 s68, v254, 26
	v_readlane_b32 s69, v254, 27
	s_add_u32 s8, s68, s8
	s_addc_u32 s35, s69, 0
	s_add_u32 s34, s8, s34
	s_addc_u32 s35, s35, 0
	s_ashr_i32 s8, s40, 16
	s_cmp_lt_i32 s8, 1
	s_cbranch_scc1 .LBB0_1247
	s_and_b64 s[40:41], s[30:31], exec
	s_cselect_b32 s67, s29, s37
	s_cselect_b32 s68, s28, s36
	s_cselect_b32 s69, s35, s39
	s_cselect_b32 s70, s34, s38
	s_add_i32 s71, s8, -2
	s_add_u32 s36, s36, 0x80080
	s_addc_u32 s37, s37, 0
	s_add_u32 s72, s38, 0x100
	s_addc_u32 s73, s39, 0
	s_mov_b32 s38, 0
	v_mov_b64_e32 v[0:1], 0
	v_mov_b64_e32 v[2:3], 0
	v_mov_b64_e32 v[4:5], 0
	v_mov_b64_e32 v[6:7], 0
	v_mov_b64_e32 v[8:9], 0
	v_mov_b64_e32 v[10:11], 0
	v_mov_b64_e32 v[12:13], 0
	v_mov_b64_e32 v[14:15], 0
	v_mov_b64_e32 v[20:21], 0
	v_mov_b64_e32 v[22:23], 0
	v_mov_b64_e32 v[28:29], 0
	v_mov_b64_e32 v[30:31], 0
	v_mov_b64_e32 v[36:37], 0
	v_mov_b64_e32 v[38:39], 0
	v_mov_b64_e32 v[44:45], 0
	v_mov_b64_e32 v[46:47], 0
	v_mov_b64_e32 v[16:17], 0
	v_mov_b64_e32 v[18:19], 0
	v_mov_b64_e32 v[24:25], 0
	v_mov_b64_e32 v[26:27], 0
	v_mov_b64_e32 v[32:33], 0
	v_mov_b64_e32 v[34:35], 0
	v_mov_b64_e32 v[40:41], 0
	v_mov_b64_e32 v[42:43], 0
	v_mov_b64_e32 v[48:49], 0
	v_mov_b64_e32 v[50:51], 0
	v_mov_b64_e32 v[52:53], 0
	v_mov_b64_e32 v[54:55], 0
	v_mov_b64_e32 v[56:57], 0
	v_mov_b64_e32 v[58:59], 0
	v_mov_b64_e32 v[60:61], 0
	v_mov_b64_e32 v[62:63], 0
	v_mov_b64_e32 v[64:65], 0
	v_mov_b64_e32 v[66:67], 0
	v_mov_b64_e32 v[68:69], 0
	v_mov_b64_e32 v[70:71], 0
	v_mov_b64_e32 v[72:73], 0
	v_mov_b64_e32 v[74:75], 0
	v_mov_b64_e32 v[76:77], 0
	v_mov_b64_e32 v[78:79], 0
	v_mov_b64_e32 v[84:85], 0
	v_mov_b64_e32 v[86:87], 0
	v_mov_b64_e32 v[92:93], 0
	v_mov_b64_e32 v[94:95], 0
	v_mov_b64_e32 v[100:101], 0
	v_mov_b64_e32 v[102:103], 0
	v_mov_b64_e32 v[108:109], 0
	v_mov_b64_e32 v[110:111], 0
	v_mov_b64_e32 v[80:81], 0
	v_mov_b64_e32 v[82:83], 0
	v_mov_b64_e32 v[88:89], 0
	v_mov_b64_e32 v[90:91], 0
	v_mov_b64_e32 v[96:97], 0
	v_mov_b64_e32 v[98:99], 0
	v_mov_b64_e32 v[104:105], 0
	v_mov_b64_e32 v[106:107], 0
	v_mov_b64_e32 v[112:113], 0
	v_mov_b64_e32 v[114:115], 0
	v_mov_b64_e32 v[116:117], 0
	v_mov_b64_e32 v[118:119], 0
	v_mov_b64_e32 v[120:121], 0
	v_mov_b64_e32 v[122:123], 0
	v_mov_b64_e32 v[124:125], 0
	v_mov_b64_e32 v[126:127], 0

.LBB0_1473:
	s_add_i32 s72, s71, -2
	s_add_u32 s73, s46, 0x100
	s_addc_u32 s74, s47, 0
	s_mov_b32 s48, 0
	v_mov_b64_e32 v[0:1], 0
	v_mov_b64_e32 v[2:3], 0
	v_mov_b64_e32 v[4:5], 0
	v_mov_b64_e32 v[6:7], 0
	v_mov_b64_e32 v[8:9], 0
	v_mov_b64_e32 v[10:11], 0
	v_mov_b64_e32 v[12:13], 0
	v_mov_b64_e32 v[14:15], 0
	v_mov_b64_e32 v[20:21], 0
	v_mov_b64_e32 v[22:23], 0
	v_mov_b64_e32 v[28:29], 0
	v_mov_b64_e32 v[30:31], 0
	v_mov_b64_e32 v[36:37], 0
	v_mov_b64_e32 v[38:39], 0
	v_mov_b64_e32 v[44:45], 0
	v_mov_b64_e32 v[46:47], 0
	v_mov_b64_e32 v[16:17], 0
	v_mov_b64_e32 v[18:19], 0
	v_mov_b64_e32 v[24:25], 0
	v_mov_b64_e32 v[26:27], 0
	v_mov_b64_e32 v[32:33], 0
	v_mov_b64_e32 v[34:35], 0
	v_mov_b64_e32 v[40:41], 0
	v_mov_b64_e32 v[42:43], 0
	v_mov_b64_e32 v[48:49], 0
	v_mov_b64_e32 v[50:51], 0
	v_mov_b64_e32 v[52:53], 0
	v_mov_b64_e32 v[54:55], 0
	v_mov_b64_e32 v[56:57], 0
	v_mov_b64_e32 v[58:59], 0
	v_mov_b64_e32 v[60:61], 0
	v_mov_b64_e32 v[62:63], 0
	v_mov_b64_e32 v[64:65], 0
	v_mov_b64_e32 v[66:67], 0
	v_mov_b64_e32 v[68:69], 0
	v_mov_b64_e32 v[70:71], 0
	v_mov_b64_e32 v[72:73], 0
	v_mov_b64_e32 v[74:75], 0
	v_mov_b64_e32 v[76:77], 0
	v_mov_b64_e32 v[78:79], 0
	v_mov_b64_e32 v[84:85], 0
	v_mov_b64_e32 v[86:87], 0
	v_mov_b64_e32 v[92:93], 0
	v_mov_b64_e32 v[94:95], 0
	v_mov_b64_e32 v[100:101], 0
	v_mov_b64_e32 v[102:103], 0
	v_mov_b64_e32 v[108:109], 0
	v_mov_b64_e32 v[110:111], 0
	v_mov_b64_e32 v[80:81], 0
	v_mov_b64_e32 v[82:83], 0
	v_mov_b64_e32 v[88:89], 0
	v_mov_b64_e32 v[90:91], 0
	v_mov_b64_e32 v[96:97], 0
	v_mov_b64_e32 v[98:99], 0
	v_mov_b64_e32 v[104:105], 0
	v_mov_b64_e32 v[106:107], 0
	v_mov_b64_e32 v[112:113], 0
	v_mov_b64_e32 v[114:115], 0
	v_mov_b64_e32 v[116:117], 0
	v_mov_b64_e32 v[118:119], 0
	v_mov_b64_e32 v[120:121], 0
	v_mov_b64_e32 v[122:123], 0
	v_mov_b64_e32 v[124:125], 0
	v_mov_b64_e32 v[126:127], 0
